# GEMM loop: static priority raise for waves 4-7 (second loop copy with priorities 2/1)
# baseline (speedup 1.0000x reference)
.LBB0_1049:
	s_xor_b64 s[88:89], s[10:11], -1
	s_mov_b32 s59, s0
	s_mov_b32 s60, s1
	s_mov_b64 s[14:15], s[4:5]
	s_mov_b64 s[2:3], s[20:21]
	s_and_b64 s[0:1], s[10:11], exec
	s_mov_b32 s61, s82
	s_cselect_b32 s67, s15, s85
	s_cselect_b32 s82, s14, s84
	s_cselect_b32 s16, s3, s7
	s_cselect_b32 s17, s2, s6
	s_lshl_b32 s4, s75, 8
	s_ashr_i32 s5, s4, 31
	s_lshl_b32 s63, s81, 8
	s_or_b32 s77, s63, 0x80
	s_lshl_b64 s[0:1], s[4:5], 1
	s_mov_b32 s58, s79
	s_add_u32 s79, s42, s0
	s_addc_u32 s92, s43, s1
	s_mov_b32 s93, 0
	s_mov_b64 s[50:51], 0
	s_mov_b64 s[64:65], 0x100
	s_mov_b64 s[30:31], s[18:19]
	s_and_b64 vcc, exec, s[44:45]
	s_cbranch_vccnz .LBB0_1051
	s_branch .Lhi_1051

.Lresc_entry:
	v_mov_b32_e32 v202, v194
	v_mov_b32_e32 v128, v198
	s_nop 0
	v_ashrrev_i32_e32 v129, 31, v128
	v_lshlrev_b64 v[212:213], 1, v[128:129]
	s_add_u32 s20, s79, s50
	s_addc_u32 s21, s92, s51
	v_add_u32_e32 v205, s63, v202
	v_mad_i64_i32 v[242:243], vcc, v205, s76, v[212:213]
	v_lshl_add_u64 v[242:243], s[20:21], 0, v[242:243]
	v_add_co_u32_e32 v242, vcc, s78, v242
	s_nop 1
	v_addc_co_u32_e32 v243, vcc, 0, v243, vcc
	global_load_dwordx4 v[128:131], v[242:243], off
	global_load_dwordx4 v[132:135], v[242:243], off offset:2048
	global_load_dwordx4 v[136:139], v[242:243], off offset:256
	global_load_dwordx4 v[140:143], v[242:243], off offset:2304
	v_add_u32_e32 v205, s63, v202
	v_add_u32_e32 v205, 16, v205
	v_mad_i64_i32 v[242:243], vcc, v205, s76, v[212:213]
	v_lshl_add_u64 v[242:243], s[20:21], 0, v[242:243]
	v_add_co_u32_e32 v242, vcc, s78, v242
	s_nop 1
	v_addc_co_u32_e32 v243, vcc, 0, v243, vcc
	global_load_dwordx4 v[144:147], v[242:243], off
	global_load_dwordx4 v[148:151], v[242:243], off offset:2048
	global_load_dwordx4 v[152:155], v[242:243], off offset:256
	global_load_dwordx4 v[156:159], v[242:243], off offset:2304
	v_add_u32_e32 v205, s63, v202
	v_add_u32_e32 v205, 32, v205
	v_mad_i64_i32 v[242:243], vcc, v205, s76, v[212:213]
	v_lshl_add_u64 v[242:243], s[20:21], 0, v[242:243]
	v_add_co_u32_e32 v242, vcc, s78, v242
	s_nop 1
	v_addc_co_u32_e32 v243, vcc, 0, v243, vcc
	global_load_dwordx4 v[160:163], v[242:243], off
	global_load_dwordx4 v[164:167], v[242:243], off offset:2048
	global_load_dwordx4 v[168:171], v[242:243], off offset:256
	global_load_dwordx4 v[172:175], v[242:243], off offset:2304
	v_add_u32_e32 v205, s63, v202
	v_add_u32_e32 v205, 48, v205
	v_mad_i64_i32 v[242:243], vcc, v205, s76, v[212:213]
	v_lshl_add_u64 v[242:243], s[20:21], 0, v[242:243]
	v_add_co_u32_e32 v242, vcc, s78, v242
	s_nop 1
	v_addc_co_u32_e32 v243, vcc, 0, v243, vcc
	global_load_dwordx4 v[176:179], v[242:243], off
	global_load_dwordx4 v[180:183], v[242:243], off offset:2048
	global_load_dwordx4 v[184:187], v[242:243], off offset:256
	global_load_dwordx4 v[188:191], v[242:243], off offset:2304
	s_waitcnt vmcnt(14)
	v_lshlrev_b32_e32 v244, 16, v128
	v_and_b32_e32 v245, 0xffff0000, v128
	v_lshlrev_b32_e32 v246, 16, v132
	v_and_b32_e32 v247, 0xffff0000, v132
	v_max_f32_e32 v244, 0x1e3ce508, v244
	v_max_f32_e32 v245, 0x1e3ce508, v245
	v_max_f32_e32 v246, 0x1e3ce508, v246
	v_max_f32_e32 v247, 0x1e3ce508, v247
	v_rcp_f32_e32 v246, v246
	v_rcp_f32_e32 v247, v247
	v_lshlrev_b32_e32 v230, 16, v129
	v_and_b32_e32 v231, 0xffff0000, v129
	v_lshlrev_b32_e32 v232, 16, v133
	v_and_b32_e32 v233, 0xffff0000, v133
	v_max_f32_e32 v230, 0x1e3ce508, v230
	v_max_f32_e32 v231, 0x1e3ce508, v231
	v_max_f32_e32 v232, 0x1e3ce508, v232
	v_max_f32_e32 v233, 0x1e3ce508, v233
	v_rcp_f32_e32 v232, v232
	v_rcp_f32_e32 v233, v233
	v_pk_mul_f32 v[244:245], v[244:245], v[246:247]
	v_pk_mul_f32 v[124:125], v[124:125], v[244:245]
	v_lshlrev_b32_e32 v244, 16, v130
	v_and_b32_e32 v245, 0xffff0000, v130
	v_lshlrev_b32_e32 v246, 16, v134
	v_and_b32_e32 v247, 0xffff0000, v134
	v_max_f32_e32 v244, 0x1e3ce508, v244
	v_max_f32_e32 v245, 0x1e3ce508, v245
	v_max_f32_e32 v246, 0x1e3ce508, v246
	v_max_f32_e32 v247, 0x1e3ce508, v247
	v_rcp_f32_e32 v246, v246
	v_rcp_f32_e32 v247, v247
	v_pk_mul_f32 v[230:231], v[230:231], v[232:233]
	v_pk_mul_f32 v[126:127], v[126:127], v[230:231]
	v_lshlrev_b32_e32 v230, 16, v131
	v_and_b32_e32 v231, 0xffff0000, v131
	v_lshlrev_b32_e32 v232, 16, v135
	v_and_b32_e32 v233, 0xffff0000, v135
	v_max_f32_e32 v230, 0x1e3ce508, v230
	v_max_f32_e32 v231, 0x1e3ce508, v231
	v_max_f32_e32 v232, 0x1e3ce508, v232
	v_max_f32_e32 v233, 0x1e3ce508, v233
	v_rcp_f32_e32 v232, v232
	v_rcp_f32_e32 v233, v233
	v_pk_mul_f32 v[244:245], v[244:245], v[246:247]
	v_pk_mul_f32 v[120:121], v[120:121], v[244:245]
	s_waitcnt vmcnt(12)
	v_lshlrev_b32_e32 v244, 16, v136
	v_and_b32_e32 v245, 0xffff0000, v136
	v_lshlrev_b32_e32 v246, 16, v140
	v_and_b32_e32 v247, 0xffff0000, v140
	v_max_f32_e32 v244, 0x1e3ce508, v244
	v_max_f32_e32 v245, 0x1e3ce508, v245
	v_max_f32_e32 v246, 0x1e3ce508, v246
	v_max_f32_e32 v247, 0x1e3ce508, v247
	v_rcp_f32_e32 v246, v246
	v_rcp_f32_e32 v247, v247
	v_pk_mul_f32 v[230:231], v[230:231], v[232:233]
	v_pk_mul_f32 v[122:123], v[122:123], v[230:231]
	v_lshlrev_b32_e32 v230, 16, v137
	v_and_b32_e32 v231, 0xffff0000, v137
	v_lshlrev_b32_e32 v232, 16, v141
	v_and_b32_e32 v233, 0xffff0000, v141
	v_max_f32_e32 v230, 0x1e3ce508, v230
	v_max_f32_e32 v231, 0x1e3ce508, v231
	v_max_f32_e32 v232, 0x1e3ce508, v232
	v_max_f32_e32 v233, 0x1e3ce508, v233
	v_rcp_f32_e32 v232, v232
	v_rcp_f32_e32 v233, v233
	v_pk_mul_f32 v[244:245], v[244:245], v[246:247]
	v_pk_mul_f32 v[92:93], v[92:93], v[244:245]
	v_lshlrev_b32_e32 v244, 16, v138
	v_and_b32_e32 v245, 0xffff0000, v138
	v_lshlrev_b32_e32 v246, 16, v142
	v_and_b32_e32 v247, 0xffff0000, v142
	v_max_f32_e32 v244, 0x1e3ce508, v244
	v_max_f32_e32 v245, 0x1e3ce508, v245
	v_max_f32_e32 v246, 0x1e3ce508, v246
	v_max_f32_e32 v247, 0x1e3ce508, v247
	v_rcp_f32_e32 v246, v246
	v_rcp_f32_e32 v247, v247
	v_pk_mul_f32 v[230:231], v[230:231], v[232:233]
	v_pk_mul_f32 v[94:95], v[94:95], v[230:231]
	v_lshlrev_b32_e32 v230, 16, v139
	v_and_b32_e32 v231, 0xffff0000, v139
	v_lshlrev_b32_e32 v232, 16, v143
	v_and_b32_e32 v233, 0xffff0000, v143
	v_max_f32_e32 v230, 0x1e3ce508, v230
	v_max_f32_e32 v231, 0x1e3ce508, v231
	v_max_f32_e32 v232, 0x1e3ce508, v232
	v_max_f32_e32 v233, 0x1e3ce508, v233
	v_rcp_f32_e32 v232, v232
	v_rcp_f32_e32 v233, v233
	v_pk_mul_f32 v[244:245], v[244:245], v[246:247]
	v_pk_mul_f32 v[88:89], v[88:89], v[244:245]
	v_pk_mul_f32 v[230:231], v[230:231], v[232:233]
	v_pk_mul_f32 v[90:91], v[90:91], v[230:231]
	v_add_u32_e32 v205, s77, v202
	v_mad_i64_i32 v[242:243], vcc, v205, s76, v[212:213]
	v_lshl_add_u64 v[242:243], s[20:21], 0, v[242:243]
	v_add_co_u32_e32 v242, vcc, s78, v242
	s_nop 1
	v_addc_co_u32_e32 v243, vcc, 0, v243, vcc
	global_load_dwordx4 v[128:131], v[242:243], off
	global_load_dwordx4 v[132:135], v[242:243], off offset:2048
	global_load_dwordx4 v[136:139], v[242:243], off offset:256
	global_load_dwordx4 v[140:143], v[242:243], off offset:2304
	s_waitcnt vmcnt(14)
	v_lshlrev_b32_e32 v244, 16, v144
	v_and_b32_e32 v245, 0xffff0000, v144
	v_lshlrev_b32_e32 v246, 16, v148
	v_and_b32_e32 v247, 0xffff0000, v148
	v_max_f32_e32 v244, 0x1e3ce508, v244
	v_max_f32_e32 v245, 0x1e3ce508, v245
	v_max_f32_e32 v246, 0x1e3ce508, v246
	v_max_f32_e32 v247, 0x1e3ce508, v247
	v_rcp_f32_e32 v246, v246
	v_rcp_f32_e32 v247, v247
	v_lshlrev_b32_e32 v230, 16, v145
	v_and_b32_e32 v231, 0xffff0000, v145
	v_lshlrev_b32_e32 v232, 16, v149
	v_and_b32_e32 v233, 0xffff0000, v149
	v_max_f32_e32 v230, 0x1e3ce508, v230
	v_max_f32_e32 v231, 0x1e3ce508, v231
	v_max_f32_e32 v232, 0x1e3ce508, v232
	v_max_f32_e32 v233, 0x1e3ce508, v233
	v_rcp_f32_e32 v232, v232
	v_rcp_f32_e32 v233, v233
	v_pk_mul_f32 v[244:245], v[244:245], v[246:247]
	v_pk_mul_f32 v[116:117], v[116:117], v[244:245]
	v_lshlrev_b32_e32 v244, 16, v146
	v_and_b32_e32 v245, 0xffff0000, v146
	v_lshlrev_b32_e32 v246, 16, v150
	v_and_b32_e32 v247, 0xffff0000, v150
	v_max_f32_e32 v244, 0x1e3ce508, v244
	v_max_f32_e32 v245, 0x1e3ce508, v245
	v_max_f32_e32 v246, 0x1e3ce508, v246
	v_max_f32_e32 v247, 0x1e3ce508, v247
	v_rcp_f32_e32 v246, v246
	v_rcp_f32_e32 v247, v247
	v_pk_mul_f32 v[230:231], v[230:231], v[232:233]
	v_pk_mul_f32 v[118:119], v[118:119], v[230:231]
	v_lshlrev_b32_e32 v230, 16, v147
	v_and_b32_e32 v231, 0xffff0000, v147
	v_lshlrev_b32_e32 v232, 16, v151
	v_and_b32_e32 v233, 0xffff0000, v151
	v_max_f32_e32 v230, 0x1e3ce508, v230
	v_max_f32_e32 v231, 0x1e3ce508, v231
	v_max_f32_e32 v232, 0x1e3ce508, v232
	v_max_f32_e32 v233, 0x1e3ce508, v233
	v_rcp_f32_e32 v232, v232
	v_rcp_f32_e32 v233, v233
	v_pk_mul_f32 v[244:245], v[244:245], v[246:247]
	v_pk_mul_f32 v[112:113], v[112:113], v[244:245]
	s_waitcnt vmcnt(12)
	v_lshlrev_b32_e32 v244, 16, v152
	v_and_b32_e32 v245, 0xffff0000, v152
	v_lshlrev_b32_e32 v246, 16, v156
	v_and_b32_e32 v247, 0xffff0000, v156
	v_max_f32_e32 v244, 0x1e3ce508, v244
	v_max_f32_e32 v245, 0x1e3ce508, v245
	v_max_f32_e32 v246, 0x1e3ce508, v246
	v_max_f32_e32 v247, 0x1e3ce508, v247
	v_rcp_f32_e32 v246, v246
	v_rcp_f32_e32 v247, v247
	v_pk_mul_f32 v[230:231], v[230:231], v[232:233]
	v_pk_mul_f32 v[114:115], v[114:115], v[230:231]
	v_lshlrev_b32_e32 v230, 16, v153
	v_and_b32_e32 v231, 0xffff0000, v153
	v_lshlrev_b32_e32 v232, 16, v157
	v_and_b32_e32 v233, 0xffff0000, v157
	v_max_f32_e32 v230, 0x1e3ce508, v230
	v_max_f32_e32 v231, 0x1e3ce508, v231
	v_max_f32_e32 v232, 0x1e3ce508, v232
	v_max_f32_e32 v233, 0x1e3ce508, v233
	v_rcp_f32_e32 v232, v232
	v_rcp_f32_e32 v233, v233
	v_pk_mul_f32 v[244:245], v[244:245], v[246:247]
	v_pk_mul_f32 v[84:85], v[84:85], v[244:245]
	v_lshlrev_b32_e32 v244, 16, v154
	v_and_b32_e32 v245, 0xffff0000, v154
	v_lshlrev_b32_e32 v246, 16, v158
	v_and_b32_e32 v247, 0xffff0000, v158
	v_max_f32_e32 v244, 0x1e3ce508, v244
	v_max_f32_e32 v245, 0x1e3ce508, v245
	v_max_f32_e32 v246, 0x1e3ce508, v246
	v_max_f32_e32 v247, 0x1e3ce508, v247
	v_rcp_f32_e32 v246, v246
	v_rcp_f32_e32 v247, v247
	v_pk_mul_f32 v[230:231], v[230:231], v[232:233]
	v_pk_mul_f32 v[86:87], v[86:87], v[230:231]
	v_lshlrev_b32_e32 v230, 16, v155
	v_and_b32_e32 v231, 0xffff0000, v155
	v_lshlrev_b32_e32 v232, 16, v159
	v_and_b32_e32 v233, 0xffff0000, v159
	v_max_f32_e32 v230, 0x1e3ce508, v230
	v_max_f32_e32 v231, 0x1e3ce508, v231
	v_max_f32_e32 v232, 0x1e3ce508, v232
	v_max_f32_e32 v233, 0x1e3ce508, v233
	v_rcp_f32_e32 v232, v232
	v_rcp_f32_e32 v233, v233
	v_pk_mul_f32 v[244:245], v[244:245], v[246:247]
	v_pk_mul_f32 v[80:81], v[80:81], v[244:245]
	v_pk_mul_f32 v[230:231], v[230:231], v[232:233]
	v_pk_mul_f32 v[82:83], v[82:83], v[230:231]
	v_add_u32_e32 v205, s77, v202
	v_add_u32_e32 v205, 16, v205
	v_mad_i64_i32 v[242:243], vcc, v205, s76, v[212:213]
	v_lshl_add_u64 v[242:243], s[20:21], 0, v[242:243]
	v_add_co_u32_e32 v242, vcc, s78, v242
	s_nop 1
	v_addc_co_u32_e32 v243, vcc, 0, v243, vcc
	global_load_dwordx4 v[144:147], v[242:243], off
	global_load_dwordx4 v[148:151], v[242:243], off offset:2048
	global_load_dwordx4 v[152:155], v[242:243], off offset:256
	global_load_dwordx4 v[156:159], v[242:243], off offset:2304
	s_waitcnt vmcnt(14)
	v_lshlrev_b32_e32 v244, 16, v160
	v_and_b32_e32 v245, 0xffff0000, v160
	v_lshlrev_b32_e32 v246, 16, v164
	v_and_b32_e32 v247, 0xffff0000, v164
	v_max_f32_e32 v244, 0x1e3ce508, v244
	v_max_f32_e32 v245, 0x1e3ce508, v245
	v_max_f32_e32 v246, 0x1e3ce508, v246
	v_max_f32_e32 v247, 0x1e3ce508, v247
	v_rcp_f32_e32 v246, v246
	v_rcp_f32_e32 v247, v247
	v_lshlrev_b32_e32 v230, 16, v161
	v_and_b32_e32 v231, 0xffff0000, v161
	v_lshlrev_b32_e32 v232, 16, v165
	v_and_b32_e32 v233, 0xffff0000, v165
	v_max_f32_e32 v230, 0x1e3ce508, v230
	v_max_f32_e32 v231, 0x1e3ce508, v231
	v_max_f32_e32 v232, 0x1e3ce508, v232
	v_max_f32_e32 v233, 0x1e3ce508, v233
	v_rcp_f32_e32 v232, v232
	v_rcp_f32_e32 v233, v233
	v_pk_mul_f32 v[244:245], v[244:245], v[246:247]
	v_pk_mul_f32 v[108:109], v[108:109], v[244:245]
	v_lshlrev_b32_e32 v244, 16, v162
	v_and_b32_e32 v245, 0xffff0000, v162
	v_lshlrev_b32_e32 v246, 16, v166
	v_and_b32_e32 v247, 0xffff0000, v166
	v_max_f32_e32 v244, 0x1e3ce508, v244
	v_max_f32_e32 v245, 0x1e3ce508, v245
	v_max_f32_e32 v246, 0x1e3ce508, v246
	v_max_f32_e32 v247, 0x1e3ce508, v247
	v_rcp_f32_e32 v246, v246
	v_rcp_f32_e32 v247, v247
	v_pk_mul_f32 v[230:231], v[230:231], v[232:233]
	v_pk_mul_f32 v[110:111], v[110:111], v[230:231]
	v_lshlrev_b32_e32 v230, 16, v163
	v_and_b32_e32 v231, 0xffff0000, v163
	v_lshlrev_b32_e32 v232, 16, v167
	v_and_b32_e32 v233, 0xffff0000, v167
	v_max_f32_e32 v230, 0x1e3ce508, v230
	v_max_f32_e32 v231, 0x1e3ce508, v231
	v_max_f32_e32 v232, 0x1e3ce508, v232
	v_max_f32_e32 v233, 0x1e3ce508, v233
	v_rcp_f32_e32 v232, v232
	v_rcp_f32_e32 v233, v233
	v_pk_mul_f32 v[244:245], v[244:245], v[246:247]
	v_pk_mul_f32 v[104:105], v[104:105], v[244:245]
	s_waitcnt vmcnt(12)
	v_lshlrev_b32_e32 v244, 16, v168
	v_and_b32_e32 v245, 0xffff0000, v168
	v_lshlrev_b32_e32 v246, 16, v172
	v_and_b32_e32 v247, 0xffff0000, v172
	v_max_f32_e32 v244, 0x1e3ce508, v244
	v_max_f32_e32 v245, 0x1e3ce508, v245
	v_max_f32_e32 v246, 0x1e3ce508, v246
	v_max_f32_e32 v247, 0x1e3ce508, v247
	v_rcp_f32_e32 v246, v246
	v_rcp_f32_e32 v247, v247
	v_pk_mul_f32 v[230:231], v[230:231], v[232:233]
	v_pk_mul_f32 v[106:107], v[106:107], v[230:231]
	v_lshlrev_b32_e32 v230, 16, v169
	v_and_b32_e32 v231, 0xffff0000, v169
	v_lshlrev_b32_e32 v232, 16, v173
	v_and_b32_e32 v233, 0xffff0000, v173
	v_max_f32_e32 v230, 0x1e3ce508, v230
	v_max_f32_e32 v231, 0x1e3ce508, v231
	v_max_f32_e32 v232, 0x1e3ce508, v232
	v_max_f32_e32 v233, 0x1e3ce508, v233
	v_rcp_f32_e32 v232, v232
	v_rcp_f32_e32 v233, v233
	v_pk_mul_f32 v[244:245], v[244:245], v[246:247]
	v_pk_mul_f32 v[76:77], v[76:77], v[244:245]
	v_lshlrev_b32_e32 v244, 16, v170
	v_and_b32_e32 v245, 0xffff0000, v170
	v_lshlrev_b32_e32 v246, 16, v174
	v_and_b32_e32 v247, 0xffff0000, v174
	v_max_f32_e32 v244, 0x1e3ce508, v244
	v_max_f32_e32 v245, 0x1e3ce508, v245
	v_max_f32_e32 v246, 0x1e3ce508, v246
	v_max_f32_e32 v247, 0x1e3ce508, v247
	v_rcp_f32_e32 v246, v246
	v_rcp_f32_e32 v247, v247
	v_pk_mul_f32 v[230:231], v[230:231], v[232:233]
	v_pk_mul_f32 v[78:79], v[78:79], v[230:231]
	v_lshlrev_b32_e32 v230, 16, v171
	v_and_b32_e32 v231, 0xffff0000, v171
	v_lshlrev_b32_e32 v232, 16, v175
	v_and_b32_e32 v233, 0xffff0000, v175
	v_max_f32_e32 v230, 0x1e3ce508, v230
	v_max_f32_e32 v231, 0x1e3ce508, v231
	v_max_f32_e32 v232, 0x1e3ce508, v232
	v_max_f32_e32 v233, 0x1e3ce508, v233
	v_rcp_f32_e32 v232, v232
	v_rcp_f32_e32 v233, v233
	v_pk_mul_f32 v[244:245], v[244:245], v[246:247]
	v_pk_mul_f32 v[72:73], v[72:73], v[244:245]
	v_pk_mul_f32 v[230:231], v[230:231], v[232:233]
	v_pk_mul_f32 v[74:75], v[74:75], v[230:231]
	v_add_u32_e32 v205, s77, v202
	v_add_u32_e32 v205, 32, v205
	v_mad_i64_i32 v[242:243], vcc, v205, s76, v[212:213]
	v_lshl_add_u64 v[242:243], s[20:21], 0, v[242:243]
	v_add_co_u32_e32 v242, vcc, s78, v242
	s_nop 1
	v_addc_co_u32_e32 v243, vcc, 0, v243, vcc
	global_load_dwordx4 v[160:163], v[242:243], off
	global_load_dwordx4 v[164:167], v[242:243], off offset:2048
	global_load_dwordx4 v[168:171], v[242:243], off offset:256
	global_load_dwordx4 v[172:175], v[242:243], off offset:2304
	s_waitcnt vmcnt(14)
	v_lshlrev_b32_e32 v244, 16, v176
	v_and_b32_e32 v245, 0xffff0000, v176
	v_lshlrev_b32_e32 v246, 16, v180
	v_and_b32_e32 v247, 0xffff0000, v180
	v_max_f32_e32 v244, 0x1e3ce508, v244
	v_max_f32_e32 v245, 0x1e3ce508, v245
	v_max_f32_e32 v246, 0x1e3ce508, v246
	v_max_f32_e32 v247, 0x1e3ce508, v247
	v_rcp_f32_e32 v246, v246
	v_rcp_f32_e32 v247, v247
	v_lshlrev_b32_e32 v230, 16, v177
	v_and_b32_e32 v231, 0xffff0000, v177
	v_lshlrev_b32_e32 v232, 16, v181
	v_and_b32_e32 v233, 0xffff0000, v181
	v_max_f32_e32 v230, 0x1e3ce508, v230
	v_max_f32_e32 v231, 0x1e3ce508, v231
	v_max_f32_e32 v232, 0x1e3ce508, v232
	v_max_f32_e32 v233, 0x1e3ce508, v233
	v_rcp_f32_e32 v232, v232
	v_rcp_f32_e32 v233, v233
	v_pk_mul_f32 v[244:245], v[244:245], v[246:247]
	v_pk_mul_f32 v[100:101], v[100:101], v[244:245]
	v_lshlrev_b32_e32 v244, 16, v178
	v_and_b32_e32 v245, 0xffff0000, v178
	v_lshlrev_b32_e32 v246, 16, v182
	v_and_b32_e32 v247, 0xffff0000, v182
	v_max_f32_e32 v244, 0x1e3ce508, v244
	v_max_f32_e32 v245, 0x1e3ce508, v245
	v_max_f32_e32 v246, 0x1e3ce508, v246
	v_max_f32_e32 v247, 0x1e3ce508, v247
	v_rcp_f32_e32 v246, v246
	v_rcp_f32_e32 v247, v247
	v_pk_mul_f32 v[230:231], v[230:231], v[232:233]
	v_pk_mul_f32 v[102:103], v[102:103], v[230:231]
	v_lshlrev_b32_e32 v230, 16, v179
	v_and_b32_e32 v231, 0xffff0000, v179
	v_lshlrev_b32_e32 v232, 16, v183
	v_and_b32_e32 v233, 0xffff0000, v183
	v_max_f32_e32 v230, 0x1e3ce508, v230
	v_max_f32_e32 v231, 0x1e3ce508, v231
	v_max_f32_e32 v232, 0x1e3ce508, v232
	v_max_f32_e32 v233, 0x1e3ce508, v233
	v_rcp_f32_e32 v232, v232
	v_rcp_f32_e32 v233, v233
	v_pk_mul_f32 v[244:245], v[244:245], v[246:247]
	v_pk_mul_f32 v[96:97], v[96:97], v[244:245]
	s_waitcnt vmcnt(12)
	v_lshlrev_b32_e32 v244, 16, v184
	v_and_b32_e32 v245, 0xffff0000, v184
	v_lshlrev_b32_e32 v246, 16, v188
	v_and_b32_e32 v247, 0xffff0000, v188
	v_max_f32_e32 v244, 0x1e3ce508, v244
	v_max_f32_e32 v245, 0x1e3ce508, v245
	v_max_f32_e32 v246, 0x1e3ce508, v246
	v_max_f32_e32 v247, 0x1e3ce508, v247
	v_rcp_f32_e32 v246, v246
	v_rcp_f32_e32 v247, v247
	v_pk_mul_f32 v[230:231], v[230:231], v[232:233]
	v_pk_mul_f32 v[98:99], v[98:99], v[230:231]
	v_lshlrev_b32_e32 v230, 16, v185
	v_and_b32_e32 v231, 0xffff0000, v185
	v_lshlrev_b32_e32 v232, 16, v189
	v_and_b32_e32 v233, 0xffff0000, v189
	v_max_f32_e32 v230, 0x1e3ce508, v230
	v_max_f32_e32 v231, 0x1e3ce508, v231
	v_max_f32_e32 v232, 0x1e3ce508, v232
	v_max_f32_e32 v233, 0x1e3ce508, v233
	v_rcp_f32_e32 v232, v232
	v_rcp_f32_e32 v233, v233
	v_pk_mul_f32 v[244:245], v[244:245], v[246:247]
	v_pk_mul_f32 v[68:69], v[68:69], v[244:245]
	v_lshlrev_b32_e32 v244, 16, v186
	v_and_b32_e32 v245, 0xffff0000, v186
	v_lshlrev_b32_e32 v246, 16, v190
	v_and_b32_e32 v247, 0xffff0000, v190
	v_max_f32_e32 v244, 0x1e3ce508, v244
	v_max_f32_e32 v245, 0x1e3ce508, v245
	v_max_f32_e32 v246, 0x1e3ce508, v246
	v_max_f32_e32 v247, 0x1e3ce508, v247
	v_rcp_f32_e32 v246, v246
	v_rcp_f32_e32 v247, v247
	v_pk_mul_f32 v[230:231], v[230:231], v[232:233]
	v_pk_mul_f32 v[70:71], v[70:71], v[230:231]
	v_lshlrev_b32_e32 v230, 16, v187
	v_and_b32_e32 v231, 0xffff0000, v187
	v_lshlrev_b32_e32 v232, 16, v191
	v_and_b32_e32 v233, 0xffff0000, v191
	v_max_f32_e32 v230, 0x1e3ce508, v230
	v_max_f32_e32 v231, 0x1e3ce508, v231
	v_max_f32_e32 v232, 0x1e3ce508, v232
	v_max_f32_e32 v233, 0x1e3ce508, v233
	v_rcp_f32_e32 v232, v232
	v_rcp_f32_e32 v233, v233
	v_pk_mul_f32 v[244:245], v[244:245], v[246:247]
	v_pk_mul_f32 v[64:65], v[64:65], v[244:245]
	v_pk_mul_f32 v[230:231], v[230:231], v[232:233]
	v_pk_mul_f32 v[66:67], v[66:67], v[230:231]
	v_add_u32_e32 v205, s77, v202
	v_add_u32_e32 v205, 48, v205
	v_mad_i64_i32 v[242:243], vcc, v205, s76, v[212:213]
	v_lshl_add_u64 v[242:243], s[20:21], 0, v[242:243]
	v_add_co_u32_e32 v242, vcc, s78, v242
	s_nop 1
	v_addc_co_u32_e32 v243, vcc, 0, v243, vcc
	global_load_dwordx4 v[176:179], v[242:243], off
	global_load_dwordx4 v[180:183], v[242:243], off offset:2048
	global_load_dwordx4 v[184:187], v[242:243], off offset:256
	global_load_dwordx4 v[188:191], v[242:243], off offset:2304
	s_waitcnt vmcnt(14)
	v_lshlrev_b32_e32 v244, 16, v128
	v_and_b32_e32 v245, 0xffff0000, v128
	v_lshlrev_b32_e32 v246, 16, v132
	v_and_b32_e32 v247, 0xffff0000, v132
	v_max_f32_e32 v244, 0x1e3ce508, v244
	v_max_f32_e32 v245, 0x1e3ce508, v245
	v_max_f32_e32 v246, 0x1e3ce508, v246
	v_max_f32_e32 v247, 0x1e3ce508, v247
	v_rcp_f32_e32 v246, v246
	v_rcp_f32_e32 v247, v247
	v_lshlrev_b32_e32 v230, 16, v129
	v_and_b32_e32 v231, 0xffff0000, v129
	v_lshlrev_b32_e32 v232, 16, v133
	v_and_b32_e32 v233, 0xffff0000, v133
	v_max_f32_e32 v230, 0x1e3ce508, v230
	v_max_f32_e32 v231, 0x1e3ce508, v231
	v_max_f32_e32 v232, 0x1e3ce508, v232
	v_max_f32_e32 v233, 0x1e3ce508, v233
	v_rcp_f32_e32 v232, v232
	v_rcp_f32_e32 v233, v233
	v_pk_mul_f32 v[244:245], v[244:245], v[246:247]
	v_pk_mul_f32 v[60:61], v[60:61], v[244:245]
	v_lshlrev_b32_e32 v244, 16, v130
	v_and_b32_e32 v245, 0xffff0000, v130
	v_lshlrev_b32_e32 v246, 16, v134
	v_and_b32_e32 v247, 0xffff0000, v134
	v_max_f32_e32 v244, 0x1e3ce508, v244
	v_max_f32_e32 v245, 0x1e3ce508, v245
	v_max_f32_e32 v246, 0x1e3ce508, v246
	v_max_f32_e32 v247, 0x1e3ce508, v247
	v_rcp_f32_e32 v246, v246
	v_rcp_f32_e32 v247, v247
	v_pk_mul_f32 v[230:231], v[230:231], v[232:233]
	v_pk_mul_f32 v[62:63], v[62:63], v[230:231]
	v_lshlrev_b32_e32 v230, 16, v131
	v_and_b32_e32 v231, 0xffff0000, v131
	v_lshlrev_b32_e32 v232, 16, v135
	v_and_b32_e32 v233, 0xffff0000, v135
	v_max_f32_e32 v230, 0x1e3ce508, v230
	v_max_f32_e32 v231, 0x1e3ce508, v231
	v_max_f32_e32 v232, 0x1e3ce508, v232
	v_max_f32_e32 v233, 0x1e3ce508, v233
	v_rcp_f32_e32 v232, v232
	v_rcp_f32_e32 v233, v233
	v_pk_mul_f32 v[244:245], v[244:245], v[246:247]
	v_pk_mul_f32 v[56:57], v[56:57], v[244:245]
	s_waitcnt vmcnt(12)
	v_lshlrev_b32_e32 v244, 16, v136
	v_and_b32_e32 v245, 0xffff0000, v136
	v_lshlrev_b32_e32 v246, 16, v140
	v_and_b32_e32 v247, 0xffff0000, v140
	v_max_f32_e32 v244, 0x1e3ce508, v244
	v_max_f32_e32 v245, 0x1e3ce508, v245
	v_max_f32_e32 v246, 0x1e3ce508, v246
	v_max_f32_e32 v247, 0x1e3ce508, v247
	v_rcp_f32_e32 v246, v246
	v_rcp_f32_e32 v247, v247
	v_pk_mul_f32 v[230:231], v[230:231], v[232:233]
	v_pk_mul_f32 v[58:59], v[58:59], v[230:231]
	v_lshlrev_b32_e32 v230, 16, v137
	v_and_b32_e32 v231, 0xffff0000, v137
	v_lshlrev_b32_e32 v232, 16, v141
	v_and_b32_e32 v233, 0xffff0000, v141
	v_max_f32_e32 v230, 0x1e3ce508, v230
	v_max_f32_e32 v231, 0x1e3ce508, v231
	v_max_f32_e32 v232, 0x1e3ce508, v232
	v_max_f32_e32 v233, 0x1e3ce508, v233
	v_rcp_f32_e32 v232, v232
	v_rcp_f32_e32 v233, v233
	v_pk_mul_f32 v[244:245], v[244:245], v[246:247]
	v_pk_mul_f32 v[28:29], v[28:29], v[244:245]
	v_lshlrev_b32_e32 v244, 16, v138
	v_and_b32_e32 v245, 0xffff0000, v138
	v_lshlrev_b32_e32 v246, 16, v142
	v_and_b32_e32 v247, 0xffff0000, v142
	v_max_f32_e32 v244, 0x1e3ce508, v244
	v_max_f32_e32 v245, 0x1e3ce508, v245
	v_max_f32_e32 v246, 0x1e3ce508, v246
	v_max_f32_e32 v247, 0x1e3ce508, v247
	v_rcp_f32_e32 v246, v246
	v_rcp_f32_e32 v247, v247
	v_pk_mul_f32 v[230:231], v[230:231], v[232:233]
	v_pk_mul_f32 v[30:31], v[30:31], v[230:231]
	v_lshlrev_b32_e32 v230, 16, v139
	v_and_b32_e32 v231, 0xffff0000, v139
	v_lshlrev_b32_e32 v232, 16, v143
	v_and_b32_e32 v233, 0xffff0000, v143
	v_max_f32_e32 v230, 0x1e3ce508, v230
	v_max_f32_e32 v231, 0x1e3ce508, v231
	v_max_f32_e32 v232, 0x1e3ce508, v232
	v_max_f32_e32 v233, 0x1e3ce508, v233
	v_rcp_f32_e32 v232, v232
	v_rcp_f32_e32 v233, v233
	v_pk_mul_f32 v[244:245], v[244:245], v[246:247]
	v_pk_mul_f32 v[24:25], v[24:25], v[244:245]
	v_pk_mul_f32 v[230:231], v[230:231], v[232:233]
	v_pk_mul_f32 v[26:27], v[26:27], v[230:231]
	s_waitcnt vmcnt(10)
	v_lshlrev_b32_e32 v244, 16, v144
	v_and_b32_e32 v245, 0xffff0000, v144
	v_lshlrev_b32_e32 v246, 16, v148
	v_and_b32_e32 v247, 0xffff0000, v148
	v_max_f32_e32 v244, 0x1e3ce508, v244
	v_max_f32_e32 v245, 0x1e3ce508, v245
	v_max_f32_e32 v246, 0x1e3ce508, v246
	v_max_f32_e32 v247, 0x1e3ce508, v247
	v_rcp_f32_e32 v246, v246
	v_rcp_f32_e32 v247, v247
	v_lshlrev_b32_e32 v230, 16, v145
	v_and_b32_e32 v231, 0xffff0000, v145
	v_lshlrev_b32_e32 v232, 16, v149
	v_and_b32_e32 v233, 0xffff0000, v149
	v_max_f32_e32 v230, 0x1e3ce508, v230
	v_max_f32_e32 v231, 0x1e3ce508, v231
	v_max_f32_e32 v232, 0x1e3ce508, v232
	v_max_f32_e32 v233, 0x1e3ce508, v233
	v_rcp_f32_e32 v232, v232
	v_rcp_f32_e32 v233, v233
	v_pk_mul_f32 v[244:245], v[244:245], v[246:247]
	v_pk_mul_f32 v[52:53], v[52:53], v[244:245]
	v_lshlrev_b32_e32 v244, 16, v146
	v_and_b32_e32 v245, 0xffff0000, v146
	v_lshlrev_b32_e32 v246, 16, v150
	v_and_b32_e32 v247, 0xffff0000, v150
	v_max_f32_e32 v244, 0x1e3ce508, v244
	v_max_f32_e32 v245, 0x1e3ce508, v245
	v_max_f32_e32 v246, 0x1e3ce508, v246
	v_max_f32_e32 v247, 0x1e3ce508, v247
	v_rcp_f32_e32 v246, v246
	v_rcp_f32_e32 v247, v247
	v_pk_mul_f32 v[230:231], v[230:231], v[232:233]
	v_pk_mul_f32 v[54:55], v[54:55], v[230:231]
	v_lshlrev_b32_e32 v230, 16, v147
	v_and_b32_e32 v231, 0xffff0000, v147
	v_lshlrev_b32_e32 v232, 16, v151
	v_and_b32_e32 v233, 0xffff0000, v151
	v_max_f32_e32 v230, 0x1e3ce508, v230
	v_max_f32_e32 v231, 0x1e3ce508, v231
	v_max_f32_e32 v232, 0x1e3ce508, v232
	v_max_f32_e32 v233, 0x1e3ce508, v233
	v_rcp_f32_e32 v232, v232
	v_rcp_f32_e32 v233, v233
	v_pk_mul_f32 v[244:245], v[244:245], v[246:247]
	v_pk_mul_f32 v[48:49], v[48:49], v[244:245]
	s_waitcnt vmcnt(8)
	v_lshlrev_b32_e32 v244, 16, v152
	v_and_b32_e32 v245, 0xffff0000, v152
	v_lshlrev_b32_e32 v246, 16, v156
	v_and_b32_e32 v247, 0xffff0000, v156
	v_max_f32_e32 v244, 0x1e3ce508, v244
	v_max_f32_e32 v245, 0x1e3ce508, v245
	v_max_f32_e32 v246, 0x1e3ce508, v246
	v_max_f32_e32 v247, 0x1e3ce508, v247
	v_rcp_f32_e32 v246, v246
	v_rcp_f32_e32 v247, v247
	v_pk_mul_f32 v[230:231], v[230:231], v[232:233]
	v_pk_mul_f32 v[50:51], v[50:51], v[230:231]
	v_lshlrev_b32_e32 v230, 16, v153
	v_and_b32_e32 v231, 0xffff0000, v153
	v_lshlrev_b32_e32 v232, 16, v157
	v_and_b32_e32 v233, 0xffff0000, v157
	v_max_f32_e32 v230, 0x1e3ce508, v230
	v_max_f32_e32 v231, 0x1e3ce508, v231
	v_max_f32_e32 v232, 0x1e3ce508, v232
	v_max_f32_e32 v233, 0x1e3ce508, v233
	v_rcp_f32_e32 v232, v232
	v_rcp_f32_e32 v233, v233
	v_pk_mul_f32 v[244:245], v[244:245], v[246:247]
	v_pk_mul_f32 v[20:21], v[20:21], v[244:245]
	v_lshlrev_b32_e32 v244, 16, v154
	v_and_b32_e32 v245, 0xffff0000, v154
	v_lshlrev_b32_e32 v246, 16, v158
	v_and_b32_e32 v247, 0xffff0000, v158
	v_max_f32_e32 v244, 0x1e3ce508, v244
	v_max_f32_e32 v245, 0x1e3ce508, v245
	v_max_f32_e32 v246, 0x1e3ce508, v246
	v_max_f32_e32 v247, 0x1e3ce508, v247
	v_rcp_f32_e32 v246, v246
	v_rcp_f32_e32 v247, v247
	v_pk_mul_f32 v[230:231], v[230:231], v[232:233]
	v_pk_mul_f32 v[22:23], v[22:23], v[230:231]
	v_lshlrev_b32_e32 v230, 16, v155
	v_and_b32_e32 v231, 0xffff0000, v155
	v_lshlrev_b32_e32 v232, 16, v159
	v_and_b32_e32 v233, 0xffff0000, v159
	v_max_f32_e32 v230, 0x1e3ce508, v230
	v_max_f32_e32 v231, 0x1e3ce508, v231
	v_max_f32_e32 v232, 0x1e3ce508, v232
	v_max_f32_e32 v233, 0x1e3ce508, v233
	v_rcp_f32_e32 v232, v232
	v_rcp_f32_e32 v233, v233
	v_pk_mul_f32 v[244:245], v[244:245], v[246:247]
	v_pk_mul_f32 v[16:17], v[16:17], v[244:245]
	v_pk_mul_f32 v[230:231], v[230:231], v[232:233]
	v_pk_mul_f32 v[18:19], v[18:19], v[230:231]
	s_waitcnt vmcnt(6)
	v_lshlrev_b32_e32 v244, 16, v160
	v_and_b32_e32 v245, 0xffff0000, v160
	v_lshlrev_b32_e32 v246, 16, v164
	v_and_b32_e32 v247, 0xffff0000, v164
	v_max_f32_e32 v244, 0x1e3ce508, v244
	v_max_f32_e32 v245, 0x1e3ce508, v245
	v_max_f32_e32 v246, 0x1e3ce508, v246
	v_max_f32_e32 v247, 0x1e3ce508, v247
	v_rcp_f32_e32 v246, v246
	v_rcp_f32_e32 v247, v247
	v_lshlrev_b32_e32 v230, 16, v161
	v_and_b32_e32 v231, 0xffff0000, v161
	v_lshlrev_b32_e32 v232, 16, v165
	v_and_b32_e32 v233, 0xffff0000, v165
	v_max_f32_e32 v230, 0x1e3ce508, v230
	v_max_f32_e32 v231, 0x1e3ce508, v231
	v_max_f32_e32 v232, 0x1e3ce508, v232
	v_max_f32_e32 v233, 0x1e3ce508, v233
	v_rcp_f32_e32 v232, v232
	v_rcp_f32_e32 v233, v233
	v_pk_mul_f32 v[244:245], v[244:245], v[246:247]
	v_pk_mul_f32 v[44:45], v[44:45], v[244:245]
	v_lshlrev_b32_e32 v244, 16, v162
	v_and_b32_e32 v245, 0xffff0000, v162
	v_lshlrev_b32_e32 v246, 16, v166
	v_and_b32_e32 v247, 0xffff0000, v166
	v_max_f32_e32 v244, 0x1e3ce508, v244
	v_max_f32_e32 v245, 0x1e3ce508, v245
	v_max_f32_e32 v246, 0x1e3ce508, v246
	v_max_f32_e32 v247, 0x1e3ce508, v247
	v_rcp_f32_e32 v246, v246
	v_rcp_f32_e32 v247, v247
	v_pk_mul_f32 v[230:231], v[230:231], v[232:233]
	v_pk_mul_f32 v[46:47], v[46:47], v[230:231]
	v_lshlrev_b32_e32 v230, 16, v163
	v_and_b32_e32 v231, 0xffff0000, v163
	v_lshlrev_b32_e32 v232, 16, v167
	v_and_b32_e32 v233, 0xffff0000, v167
	v_max_f32_e32 v230, 0x1e3ce508, v230
	v_max_f32_e32 v231, 0x1e3ce508, v231
	v_max_f32_e32 v232, 0x1e3ce508, v232
	v_max_f32_e32 v233, 0x1e3ce508, v233
	v_rcp_f32_e32 v232, v232
	v_rcp_f32_e32 v233, v233
	v_pk_mul_f32 v[244:245], v[244:245], v[246:247]
	v_pk_mul_f32 v[40:41], v[40:41], v[244:245]
	s_waitcnt vmcnt(4)
	v_lshlrev_b32_e32 v244, 16, v168
	v_and_b32_e32 v245, 0xffff0000, v168
	v_lshlrev_b32_e32 v246, 16, v172
	v_and_b32_e32 v247, 0xffff0000, v172
	v_max_f32_e32 v244, 0x1e3ce508, v244
	v_max_f32_e32 v245, 0x1e3ce508, v245
	v_max_f32_e32 v246, 0x1e3ce508, v246
	v_max_f32_e32 v247, 0x1e3ce508, v247
	v_rcp_f32_e32 v246, v246
	v_rcp_f32_e32 v247, v247
	v_pk_mul_f32 v[230:231], v[230:231], v[232:233]
	v_pk_mul_f32 v[42:43], v[42:43], v[230:231]
	v_lshlrev_b32_e32 v230, 16, v169
	v_and_b32_e32 v231, 0xffff0000, v169
	v_lshlrev_b32_e32 v232, 16, v173
	v_and_b32_e32 v233, 0xffff0000, v173
	v_max_f32_e32 v230, 0x1e3ce508, v230
	v_max_f32_e32 v231, 0x1e3ce508, v231
	v_max_f32_e32 v232, 0x1e3ce508, v232
	v_max_f32_e32 v233, 0x1e3ce508, v233
	v_rcp_f32_e32 v232, v232
	v_rcp_f32_e32 v233, v233
	v_pk_mul_f32 v[244:245], v[244:245], v[246:247]
	v_pk_mul_f32 v[12:13], v[12:13], v[244:245]
	v_lshlrev_b32_e32 v244, 16, v170
	v_and_b32_e32 v245, 0xffff0000, v170
	v_lshlrev_b32_e32 v246, 16, v174
	v_and_b32_e32 v247, 0xffff0000, v174
	v_max_f32_e32 v244, 0x1e3ce508, v244
	v_max_f32_e32 v245, 0x1e3ce508, v245
	v_max_f32_e32 v246, 0x1e3ce508, v246
	v_max_f32_e32 v247, 0x1e3ce508, v247
	v_rcp_f32_e32 v246, v246
	v_rcp_f32_e32 v247, v247
	v_pk_mul_f32 v[230:231], v[230:231], v[232:233]
	v_pk_mul_f32 v[14:15], v[14:15], v[230:231]
	v_lshlrev_b32_e32 v230, 16, v171
	v_and_b32_e32 v231, 0xffff0000, v171
	v_lshlrev_b32_e32 v232, 16, v175
	v_and_b32_e32 v233, 0xffff0000, v175
	v_max_f32_e32 v230, 0x1e3ce508, v230
	v_max_f32_e32 v231, 0x1e3ce508, v231
	v_max_f32_e32 v232, 0x1e3ce508, v232
	v_max_f32_e32 v233, 0x1e3ce508, v233
	v_rcp_f32_e32 v232, v232
	v_rcp_f32_e32 v233, v233
	v_pk_mul_f32 v[244:245], v[244:245], v[246:247]
	v_pk_mul_f32 v[8:9], v[8:9], v[244:245]
	v_pk_mul_f32 v[230:231], v[230:231], v[232:233]
	v_pk_mul_f32 v[10:11], v[10:11], v[230:231]
	s_waitcnt vmcnt(2)
	v_lshlrev_b32_e32 v244, 16, v176
	v_and_b32_e32 v245, 0xffff0000, v176
	v_lshlrev_b32_e32 v246, 16, v180
	v_and_b32_e32 v247, 0xffff0000, v180
	v_max_f32_e32 v244, 0x1e3ce508, v244
	v_max_f32_e32 v245, 0x1e3ce508, v245
	v_max_f32_e32 v246, 0x1e3ce508, v246
	v_max_f32_e32 v247, 0x1e3ce508, v247
	v_rcp_f32_e32 v246, v246
	v_rcp_f32_e32 v247, v247
	v_lshlrev_b32_e32 v230, 16, v177
	v_and_b32_e32 v231, 0xffff0000, v177
	v_lshlrev_b32_e32 v232, 16, v181
	v_and_b32_e32 v233, 0xffff0000, v181
	v_max_f32_e32 v230, 0x1e3ce508, v230
	v_max_f32_e32 v231, 0x1e3ce508, v231
	v_max_f32_e32 v232, 0x1e3ce508, v232
	v_max_f32_e32 v233, 0x1e3ce508, v233
	v_rcp_f32_e32 v232, v232
	v_rcp_f32_e32 v233, v233
	v_pk_mul_f32 v[244:245], v[244:245], v[246:247]
	v_pk_mul_f32 v[36:37], v[36:37], v[244:245]
	v_lshlrev_b32_e32 v244, 16, v178
	v_and_b32_e32 v245, 0xffff0000, v178
	v_lshlrev_b32_e32 v246, 16, v182
	v_and_b32_e32 v247, 0xffff0000, v182
	v_max_f32_e32 v244, 0x1e3ce508, v244
	v_max_f32_e32 v245, 0x1e3ce508, v245
	v_max_f32_e32 v246, 0x1e3ce508, v246
	v_max_f32_e32 v247, 0x1e3ce508, v247
	v_rcp_f32_e32 v246, v246
	v_rcp_f32_e32 v247, v247
	v_pk_mul_f32 v[230:231], v[230:231], v[232:233]
	v_pk_mul_f32 v[38:39], v[38:39], v[230:231]
	v_lshlrev_b32_e32 v230, 16, v179
	v_and_b32_e32 v231, 0xffff0000, v179
	v_lshlrev_b32_e32 v232, 16, v183
	v_and_b32_e32 v233, 0xffff0000, v183
	v_max_f32_e32 v230, 0x1e3ce508, v230
	v_max_f32_e32 v231, 0x1e3ce508, v231
	v_max_f32_e32 v232, 0x1e3ce508, v232
	v_max_f32_e32 v233, 0x1e3ce508, v233
	v_rcp_f32_e32 v232, v232
	v_rcp_f32_e32 v233, v233
	v_pk_mul_f32 v[244:245], v[244:245], v[246:247]
	v_pk_mul_f32 v[32:33], v[32:33], v[244:245]
	s_waitcnt vmcnt(0)
	v_lshlrev_b32_e32 v244, 16, v184
	v_and_b32_e32 v245, 0xffff0000, v184
	v_lshlrev_b32_e32 v246, 16, v188
	v_and_b32_e32 v247, 0xffff0000, v188
	v_max_f32_e32 v244, 0x1e3ce508, v244
	v_max_f32_e32 v245, 0x1e3ce508, v245
	v_max_f32_e32 v246, 0x1e3ce508, v246
	v_max_f32_e32 v247, 0x1e3ce508, v247
	v_rcp_f32_e32 v246, v246
	v_rcp_f32_e32 v247, v247
	v_pk_mul_f32 v[230:231], v[230:231], v[232:233]
	v_pk_mul_f32 v[34:35], v[34:35], v[230:231]
	v_lshlrev_b32_e32 v230, 16, v185
	v_and_b32_e32 v231, 0xffff0000, v185
	v_lshlrev_b32_e32 v232, 16, v189
	v_and_b32_e32 v233, 0xffff0000, v189
	v_max_f32_e32 v230, 0x1e3ce508, v230
	v_max_f32_e32 v231, 0x1e3ce508, v231
	v_max_f32_e32 v232, 0x1e3ce508, v232
	v_max_f32_e32 v233, 0x1e3ce508, v233
	v_rcp_f32_e32 v232, v232
	v_rcp_f32_e32 v233, v233
	v_pk_mul_f32 v[244:245], v[244:245], v[246:247]
	v_pk_mul_f32 v[4:5], v[4:5], v[244:245]
	v_lshlrev_b32_e32 v244, 16, v186
	v_and_b32_e32 v245, 0xffff0000, v186
	v_lshlrev_b32_e32 v246, 16, v190
	v_and_b32_e32 v247, 0xffff0000, v190
	v_max_f32_e32 v244, 0x1e3ce508, v244
	v_max_f32_e32 v245, 0x1e3ce508, v245
	v_max_f32_e32 v246, 0x1e3ce508, v246
	v_max_f32_e32 v247, 0x1e3ce508, v247
	v_rcp_f32_e32 v246, v246
	v_rcp_f32_e32 v247, v247
	v_pk_mul_f32 v[230:231], v[230:231], v[232:233]
	v_pk_mul_f32 v[6:7], v[6:7], v[230:231]
	v_lshlrev_b32_e32 v230, 16, v187
	v_and_b32_e32 v231, 0xffff0000, v187
	v_lshlrev_b32_e32 v232, 16, v191
	v_and_b32_e32 v233, 0xffff0000, v191
	v_max_f32_e32 v230, 0x1e3ce508, v230
	v_max_f32_e32 v231, 0x1e3ce508, v231
	v_max_f32_e32 v232, 0x1e3ce508, v232
	v_max_f32_e32 v233, 0x1e3ce508, v233
	v_rcp_f32_e32 v232, v232
	v_rcp_f32_e32 v233, v233
	v_pk_mul_f32 v[244:245], v[244:245], v[246:247]
	v_pk_mul_f32 v[0:1], v[0:1], v[244:245]
	v_pk_mul_f32 v[230:231], v[230:231], v[232:233]
	v_pk_mul_f32 v[2:3], v[2:3], v[230:231]
	s_and_b64 vcc, exec, s[44:45]
	s_cbranch_vccnz .LBB0_1050
	s_branch .Lhi_1050
.Lhi_1050:
	s_add_i32 s93, s93, 2
	s_add_u32 s20, s84, s64
	s_addc_u32 s21, s85, s65
	s_add_u32 s54, s6, s64
	s_addc_u32 s55, s7, s65
	s_add_i32 s94, 0, 0x10000
	s_cmp_eq_u32 s9, s50
	s_cselect_b32 s21, s67, s21
	s_cselect_b32 s20, s82, s20
	s_cselect_b32 vcc_hi, s16, s55
	s_cselect_b32 vcc_lo, s17, s54
	s_add_i32 s72, 0, 0x14000
	v_add_u32_e32 v140, s94, v197
	v_add_u32_e32 v156, s72, v197
	ds_read_b128 v[128:131], v140
	ds_read_b128 v[132:135], v140 offset:1024
	ds_read_b128 v[136:139], v140 offset:2048
	ds_read_b128 v[140:143], v140 offset:3072
	ds_read_b128 v[144:147], v156
	ds_read_b128 v[148:151], v156 offset:1024
	ds_read_b128 v[152:155], v156 offset:2048
	ds_read_b128 v[156:159], v156 offset:3072
	s_add_i32 m0, s53, 0xc000
	s_add_u32 s54, s84, s30
	s_addc_u32 s55, s85, s31
	ds_read_b128 v[160:163], v200
	ds_read_b128 v[164:167], v200 offset:1024
	ds_read_b128 v[168:171], v200 offset:2048
	ds_read_b128 v[172:175], v200 offset:3072
	ds_read_b128 v[176:179], v200 offset:4096
	ds_read_b128 v[180:183], v200 offset:5120
	ds_read_b128 v[184:187], v200 offset:6144
	ds_read_b128 v[188:191], v200 offset:7168
	global_load_lds_dwordx4 v192, s[54:55]
	s_add_i32 m0, s53, 0xe000
	v_mov_b32_e32 v207, v193
	global_load_lds_dwordx4 v206, s[54:55]
	s_waitcnt vmcnt(8)
	s_waitcnt lgkmcnt(0)
	s_barrier
	s_setprio 2
	s_waitcnt lgkmcnt(0)
	v_mfma_f32_16x16x32_bf16 v[124:127], v[128:131], v[160:163], v[124:127]
	v_mfma_f32_16x16x32_bf16 v[120:123], v[136:139], v[160:163], v[120:123]
	v_mfma_f32_16x16x32_bf16 v[116:119], v[128:131], v[168:171], v[116:119]
	v_mfma_f32_16x16x32_bf16 v[112:115], v[136:139], v[168:171], v[112:115]
	v_mfma_f32_16x16x32_bf16 v[108:111], v[128:131], v[176:179], v[108:111]
	v_mfma_f32_16x16x32_bf16 v[104:107], v[136:139], v[176:179], v[104:107]
	v_mfma_f32_16x16x32_bf16 v[100:103], v[128:131], v[184:187], v[100:103]
	v_mfma_f32_16x16x32_bf16 v[96:99], v[136:139], v[184:187], v[96:99]
	v_mfma_f32_16x16x32_bf16 v[124:127], v[132:135], v[164:167], v[124:127]
	v_mfma_f32_16x16x32_bf16 v[120:123], v[140:143], v[164:167], v[120:123]
	v_mfma_f32_16x16x32_bf16 v[116:119], v[132:135], v[172:175], v[116:119]
	v_mfma_f32_16x16x32_bf16 v[112:115], v[140:143], v[172:175], v[112:115]
	v_mfma_f32_16x16x32_bf16 v[108:111], v[132:135], v[180:183], v[108:111]
	v_mfma_f32_16x16x32_bf16 v[104:107], v[140:143], v[180:183], v[104:107]
	v_mfma_f32_16x16x32_bf16 v[100:103], v[132:135], v[188:191], v[100:103]
	v_mfma_f32_16x16x32_bf16 v[96:99], v[140:143], v[188:191], v[96:99]
	s_setprio 1
	s_setprio 2
	v_mfma_f32_16x16x32_bf16 v[92:95], v[144:147], v[160:163], v[92:95]
	v_mfma_f32_16x16x32_bf16 v[88:91], v[152:155], v[160:163], v[88:91]
	v_mfma_f32_16x16x32_bf16 v[84:87], v[144:147], v[168:171], v[84:87]
	v_mfma_f32_16x16x32_bf16 v[80:83], v[152:155], v[168:171], v[80:83]
	v_mfma_f32_16x16x32_bf16 v[76:79], v[144:147], v[176:179], v[76:79]
	v_mfma_f32_16x16x32_bf16 v[72:75], v[152:155], v[176:179], v[72:75]
	v_mfma_f32_16x16x32_bf16 v[68:71], v[144:147], v[184:187], v[68:71]
	v_mfma_f32_16x16x32_bf16 v[64:67], v[152:155], v[184:187], v[64:67]
	v_mfma_f32_16x16x32_bf16 v[92:95], v[148:151], v[164:167], v[92:95]
	v_mfma_f32_16x16x32_bf16 v[88:91], v[156:159], v[164:167], v[88:91]
	v_mfma_f32_16x16x32_bf16 v[84:87], v[148:151], v[172:175], v[84:87]
	v_mfma_f32_16x16x32_bf16 v[80:83], v[156:159], v[172:175], v[80:83]
	v_mfma_f32_16x16x32_bf16 v[76:79], v[148:151], v[180:183], v[76:79]
	v_mfma_f32_16x16x32_bf16 v[72:75], v[156:159], v[180:183], v[72:75]
	v_mfma_f32_16x16x32_bf16 v[68:71], v[148:151], v[188:191], v[68:71]
	v_mfma_f32_16x16x32_bf16 v[64:67], v[156:159], v[188:191], v[64:67]
	s_setprio 1
	s_barrier
	s_add_i32 s54, s94, s29
	s_mov_b32 m0, s54
	ds_read_b128 v[160:163], v200 offset:16384
	ds_read_b128 v[164:167], v200 offset:17408
	ds_read_b128 v[168:171], v200 offset:18432
	ds_read_b128 v[172:175], v200 offset:19456
	ds_read_b128 v[176:179], v200 offset:20480
	ds_read_b128 v[180:183], v200 offset:21504
	ds_read_b128 v[184:187], v200 offset:22528
	ds_read_b128 v[188:191], v200 offset:23552
	global_load_lds_dwordx4 v204, vcc
	s_add_i32 m0, s54, 0x2000
	s_add_u32 s54, vcc_lo, s73
	s_addc_u32 s55, vcc_hi, 0
	s_add_i32 s72, s72, s29
	global_load_lds_dwordx4 v208, vcc
	s_mov_b32 m0, s72
	v_mov_b32_e32 v205, v193
	global_load_lds_dwordx4 v204, s[54:55]
	s_add_i32 m0, s72, 0x2000
	v_mov_b32_e32 v209, v193
	global_load_lds_dwordx4 v208, s[54:55]
	s_mov_b32 m0, s53
	v_lshl_add_u64 v[212:213], vcc, 0, v[204:205]
	global_load_lds_dwordx4 v192, s[20:21]
	s_mov_b32 m0, s52
	v_lshl_add_u64 v[242:243], vcc, 0, v[208:209]
	global_load_lds_dwordx4 v206, s[20:21]
	s_waitcnt vmcnt(8)
	s_waitcnt lgkmcnt(0)
	v_lshl_add_u64 v[244:245], s[54:55], 0, v[204:205]
	v_lshl_add_u64 v[246:247], s[54:55], 0, v[208:209]
	v_lshl_add_u64 v[230:231], s[20:21], 0, v[192:193]
	v_lshl_add_u64 v[232:233], s[20:21], 0, v[206:207]
	s_barrier
	s_setprio 2
	s_waitcnt lgkmcnt(0)
	v_mfma_f32_16x16x32_bf16 v[60:63], v[128:131], v[160:163], v[60:63]
	v_mfma_f32_16x16x32_bf16 v[56:59], v[136:139], v[160:163], v[56:59]
	v_mfma_f32_16x16x32_bf16 v[52:55], v[128:131], v[168:171], v[52:55]
	v_mfma_f32_16x16x32_bf16 v[48:51], v[136:139], v[168:171], v[48:51]
	v_mfma_f32_16x16x32_bf16 v[44:47], v[128:131], v[176:179], v[44:47]
	v_mfma_f32_16x16x32_bf16 v[40:43], v[136:139], v[176:179], v[40:43]
	v_mfma_f32_16x16x32_bf16 v[36:39], v[128:131], v[184:187], v[36:39]
	v_mfma_f32_16x16x32_bf16 v[32:35], v[136:139], v[184:187], v[32:35]
	v_mfma_f32_16x16x32_bf16 v[60:63], v[132:135], v[164:167], v[60:63]
	v_mfma_f32_16x16x32_bf16 v[56:59], v[140:143], v[164:167], v[56:59]
	v_mfma_f32_16x16x32_bf16 v[52:55], v[132:135], v[172:175], v[52:55]
	v_mfma_f32_16x16x32_bf16 v[48:51], v[140:143], v[172:175], v[48:51]
	v_mfma_f32_16x16x32_bf16 v[44:47], v[132:135], v[180:183], v[44:47]
	v_mfma_f32_16x16x32_bf16 v[40:43], v[140:143], v[180:183], v[40:43]
	v_mfma_f32_16x16x32_bf16 v[36:39], v[132:135], v[188:191], v[36:39]
	v_mfma_f32_16x16x32_bf16 v[32:35], v[140:143], v[188:191], v[32:35]
	s_setprio 1
	s_setprio 2
	v_mfma_f32_16x16x32_bf16 v[28:31], v[144:147], v[160:163], v[28:31]
	v_mfma_f32_16x16x32_bf16 v[24:27], v[152:155], v[160:163], v[24:27]
	v_mfma_f32_16x16x32_bf16 v[20:23], v[144:147], v[168:171], v[20:23]
	v_mfma_f32_16x16x32_bf16 v[16:19], v[152:155], v[168:171], v[16:19]
	v_mfma_f32_16x16x32_bf16 v[12:15], v[144:147], v[176:179], v[12:15]
	v_mfma_f32_16x16x32_bf16 v[8:11], v[152:155], v[176:179], v[8:11]
	v_mfma_f32_16x16x32_bf16 v[4:7], v[144:147], v[184:187], v[4:7]
	v_mfma_f32_16x16x32_bf16 v[0:3], v[152:155], v[184:187], v[0:3]
	v_mfma_f32_16x16x32_bf16 v[28:31], v[148:151], v[164:167], v[28:31]
	v_mfma_f32_16x16x32_bf16 v[24:27], v[156:159], v[164:167], v[24:27]
	v_mfma_f32_16x16x32_bf16 v[20:23], v[148:151], v[172:175], v[20:23]
	v_mfma_f32_16x16x32_bf16 v[16:19], v[156:159], v[172:175], v[16:19]
	v_mfma_f32_16x16x32_bf16 v[12:15], v[148:151], v[180:183], v[12:15]
	v_mfma_f32_16x16x32_bf16 v[8:11], v[156:159], v[180:183], v[8:11]
	v_mfma_f32_16x16x32_bf16 v[4:7], v[148:151], v[188:191], v[4:7]
	v_mfma_f32_16x16x32_bf16 v[0:3], v[156:159], v[188:191], v[0:3]
	s_setprio 1
	s_barrier
	s_add_i32 s54, 0, 0x18000
	s_add_i32 s55, 0, 0x1c000
	v_add_u32_e32 v140, s54, v197
	v_add_u32_e32 v156, s55, v197
	ds_read_b128 v[128:131], v140
	ds_read_b128 v[132:135], v140 offset:1024
	ds_read_b128 v[136:139], v140 offset:2048
	ds_read_b128 v[140:143], v140 offset:3072
	ds_read_b128 v[144:147], v156
	ds_read_b128 v[148:151], v156 offset:1024
	ds_read_b128 v[152:155], v156 offset:2048
	ds_read_b128 v[156:159], v156 offset:3072
	s_add_u32 s20, s20, s73
	s_addc_u32 s21, s21, 0
	s_mov_b32 m0, s33
	ds_read_b128 v[160:163], v200 offset:32768
	ds_read_b128 v[164:167], v200 offset:33792
	ds_read_b128 v[168:171], v200 offset:34816
	ds_read_b128 v[172:175], v200 offset:35840
	ds_read_b128 v[176:179], v200 offset:36864
	ds_read_b128 v[180:183], v200 offset:37888
	ds_read_b128 v[184:187], v200 offset:38912
	ds_read_b128 v[188:191], v200 offset:39936
	global_load_lds_dwordx4 v192, s[20:21]
	s_mov_b32 m0, s68
	s_nop 0
	global_load_lds_dwordx4 v206, s[20:21]
	s_waitcnt vmcnt(8)
	s_waitcnt lgkmcnt(0)
	s_barrier
	s_setprio 2
	s_waitcnt lgkmcnt(0)
	v_mfma_f32_16x16x32_bf16 v[124:127], v[128:131], v[160:163], v[124:127]
	v_mfma_f32_16x16x32_bf16 v[120:123], v[136:139], v[160:163], v[120:123]
	v_mfma_f32_16x16x32_bf16 v[116:119], v[128:131], v[168:171], v[116:119]
	v_mfma_f32_16x16x32_bf16 v[112:115], v[136:139], v[168:171], v[112:115]
	v_mfma_f32_16x16x32_bf16 v[108:111], v[128:131], v[176:179], v[108:111]
	v_mfma_f32_16x16x32_bf16 v[104:107], v[136:139], v[176:179], v[104:107]
	v_mfma_f32_16x16x32_bf16 v[100:103], v[128:131], v[184:187], v[100:103]
	v_mfma_f32_16x16x32_bf16 v[96:99], v[136:139], v[184:187], v[96:99]
	v_mfma_f32_16x16x32_bf16 v[124:127], v[132:135], v[164:167], v[124:127]
	v_mfma_f32_16x16x32_bf16 v[120:123], v[140:143], v[164:167], v[120:123]
	v_mfma_f32_16x16x32_bf16 v[116:119], v[132:135], v[172:175], v[116:119]
	v_mfma_f32_16x16x32_bf16 v[112:115], v[140:143], v[172:175], v[112:115]
	v_mfma_f32_16x16x32_bf16 v[108:111], v[132:135], v[180:183], v[108:111]
	v_mfma_f32_16x16x32_bf16 v[104:107], v[140:143], v[180:183], v[104:107]
	v_mfma_f32_16x16x32_bf16 v[100:103], v[132:135], v[188:191], v[100:103]
	v_mfma_f32_16x16x32_bf16 v[96:99], v[140:143], v[188:191], v[96:99]
	s_setprio 1
	s_setprio 2
	v_mfma_f32_16x16x32_bf16 v[92:95], v[144:147], v[160:163], v[92:95]
	v_mfma_f32_16x16x32_bf16 v[88:91], v[152:155], v[160:163], v[88:91]
	v_mfma_f32_16x16x32_bf16 v[84:87], v[144:147], v[168:171], v[84:87]
	v_mfma_f32_16x16x32_bf16 v[80:83], v[152:155], v[168:171], v[80:83]
	v_mfma_f32_16x16x32_bf16 v[76:79], v[144:147], v[176:179], v[76:79]
	v_mfma_f32_16x16x32_bf16 v[72:75], v[152:155], v[176:179], v[72:75]
	v_mfma_f32_16x16x32_bf16 v[68:71], v[144:147], v[184:187], v[68:71]
	v_mfma_f32_16x16x32_bf16 v[64:67], v[152:155], v[184:187], v[64:67]
	v_mfma_f32_16x16x32_bf16 v[92:95], v[148:151], v[164:167], v[92:95]
	v_mfma_f32_16x16x32_bf16 v[88:91], v[156:159], v[164:167], v[88:91]
	v_mfma_f32_16x16x32_bf16 v[84:87], v[148:151], v[172:175], v[84:87]
	v_mfma_f32_16x16x32_bf16 v[80:83], v[156:159], v[172:175], v[80:83]
	v_mfma_f32_16x16x32_bf16 v[76:79], v[148:151], v[180:183], v[76:79]
	v_mfma_f32_16x16x32_bf16 v[72:75], v[156:159], v[180:183], v[72:75]
	v_mfma_f32_16x16x32_bf16 v[68:71], v[148:151], v[188:191], v[68:71]
	v_mfma_f32_16x16x32_bf16 v[64:67], v[156:159], v[188:191], v[64:67]
	s_setprio 1
	s_barrier
	s_add_i32 s20, s54, s29
	v_lshl_add_u64 v[212:213], v[212:213], 0, s[46:47]
	s_mov_b32 m0, s20
	ds_read_b128 v[160:163], v200 offset:49152
	ds_read_b128 v[164:167], v200 offset:50176
	ds_read_b128 v[168:171], v200 offset:51200
	ds_read_b128 v[172:175], v200 offset:52224
	ds_read_b128 v[176:179], v200 offset:53248
	ds_read_b128 v[180:183], v200 offset:54272
	ds_read_b128 v[184:187], v200 offset:55296
	ds_read_b128 v[188:191], v200 offset:56320
	global_load_lds_dwordx4 v[212:213], off
	v_lshl_add_u64 v[212:213], v[242:243], 0, s[46:47]
	s_add_i32 m0, s20, 0x2000
	s_add_i32 s20, s55, s29
	global_load_lds_dwordx4 v[212:213], off
	v_lshl_add_u64 v[212:213], v[244:245], 0, s[46:47]
	s_mov_b32 m0, s20
	s_nop 0
	global_load_lds_dwordx4 v[212:213], off
	v_lshl_add_u64 v[212:213], v[246:247], 0, s[46:47]
	s_add_i32 m0, s20, 0x2000
	s_nop 0
	global_load_lds_dwordx4 v[212:213], off
	v_lshl_add_u64 v[212:213], v[230:231], 0, s[46:47]
	s_mov_b32 m0, s69
	s_nop 0
	global_load_lds_dwordx4 v[212:213], off
	v_lshl_add_u64 v[212:213], v[232:233], 0, s[46:47]
	s_mov_b32 m0, s70
	s_nop 0
	global_load_lds_dwordx4 v[212:213], off
	s_waitcnt vmcnt(8)
	s_waitcnt lgkmcnt(0)
	s_barrier
	s_setprio 2
	s_waitcnt lgkmcnt(0)
	v_mfma_f32_16x16x32_bf16 v[60:63], v[128:131], v[160:163], v[60:63]
	v_mfma_f32_16x16x32_bf16 v[56:59], v[136:139], v[160:163], v[56:59]
	v_mfma_f32_16x16x32_bf16 v[52:55], v[128:131], v[168:171], v[52:55]
	v_mfma_f32_16x16x32_bf16 v[48:51], v[136:139], v[168:171], v[48:51]
	v_mfma_f32_16x16x32_bf16 v[44:47], v[128:131], v[176:179], v[44:47]
	v_mfma_f32_16x16x32_bf16 v[40:43], v[136:139], v[176:179], v[40:43]
	v_mfma_f32_16x16x32_bf16 v[36:39], v[128:131], v[184:187], v[36:39]
	v_mfma_f32_16x16x32_bf16 v[32:35], v[136:139], v[184:187], v[32:35]
	v_mfma_f32_16x16x32_bf16 v[60:63], v[132:135], v[164:167], v[60:63]
	v_mfma_f32_16x16x32_bf16 v[56:59], v[140:143], v[164:167], v[56:59]
	v_mfma_f32_16x16x32_bf16 v[52:55], v[132:135], v[172:175], v[52:55]
	v_mfma_f32_16x16x32_bf16 v[48:51], v[140:143], v[172:175], v[48:51]
	v_mfma_f32_16x16x32_bf16 v[44:47], v[132:135], v[180:183], v[44:47]
	v_mfma_f32_16x16x32_bf16 v[40:43], v[140:143], v[180:183], v[40:43]
	v_mfma_f32_16x16x32_bf16 v[36:39], v[132:135], v[188:191], v[36:39]
	v_mfma_f32_16x16x32_bf16 v[32:35], v[140:143], v[188:191], v[32:35]
	s_setprio 1
	s_setprio 2
	v_mfma_f32_16x16x32_bf16 v[28:31], v[144:147], v[160:163], v[28:31]
	v_mfma_f32_16x16x32_bf16 v[24:27], v[152:155], v[160:163], v[24:27]
	v_mfma_f32_16x16x32_bf16 v[20:23], v[144:147], v[168:171], v[20:23]
	v_mfma_f32_16x16x32_bf16 v[16:19], v[152:155], v[168:171], v[16:19]
	v_mfma_f32_16x16x32_bf16 v[12:15], v[144:147], v[176:179], v[12:15]
	v_mfma_f32_16x16x32_bf16 v[8:11], v[152:155], v[176:179], v[8:11]
	v_mfma_f32_16x16x32_bf16 v[4:7], v[144:147], v[184:187], v[4:7]
	v_mfma_f32_16x16x32_bf16 v[0:3], v[152:155], v[184:187], v[0:3]
	v_mfma_f32_16x16x32_bf16 v[28:31], v[148:151], v[164:167], v[28:31]
	v_mfma_f32_16x16x32_bf16 v[24:27], v[156:159], v[164:167], v[24:27]
	v_mfma_f32_16x16x32_bf16 v[20:23], v[148:151], v[172:175], v[20:23]
	v_mfma_f32_16x16x32_bf16 v[16:19], v[156:159], v[172:175], v[16:19]
	v_mfma_f32_16x16x32_bf16 v[12:15], v[148:151], v[180:183], v[12:15]
	v_mfma_f32_16x16x32_bf16 v[8:11], v[156:159], v[180:183], v[8:11]
	v_mfma_f32_16x16x32_bf16 v[4:7], v[148:151], v[188:191], v[4:7]
	v_mfma_f32_16x16x32_bf16 v[0:3], v[156:159], v[188:191], v[0:3]
	s_setprio 1
	s_barrier
	s_add_u32 s50, s50, 0x200
	s_addc_u32 s51, s51, 0
	s_add_u32 s64, s64, 0x100
	s_addc_u32 s65, s65, 0
	s_add_u32 s30, s30, 0x100
	s_addc_u32 s31, s31, 0
	s_cmp_ge_u32 s93, s8
	s_cbranch_scc1 .LBB0_1053
.Lhi_1051:
	s_cmp_eq_u32 s50, 0
	s_cselect_b64 s[20:21], -1, 0
	s_or_b64 s[20:21], s[34:35], s[20:21]
	s_and_b32 s54, s93, 6
	s_cmp_lg_u32 s54, 0
	s_cselect_b64 vcc, -1, 0
	s_or_b64 s[20:21], s[20:21], vcc
	s_and_b64 vcc, exec, s[20:21]
	s_cbranch_vccnz .Lhi_1050
	s_branch .Lresc_entry
.LBB0_1053:
	s_setprio 0
	s_and_b64 vcc, exec, s[44:45]
	s_cbranch_vccz .LBB0_1055
	s_barrier
